# v38 with the P-stage MFMA-to-VALU distance restored (s_nop 11)
# baseline (speedup 1.0000x reference)
; __device__ __forceinline__ float bf2f(unsigned h) { return __uint_as_float(h << 16); }
; __device__ __forceinline__ void mla_unit(char* lds, const bf16_t* __restrict__ Qp, const bf16_t* __restrict__ Knp, const bf16_t* __restrict__ Vp, ...
;     ...
;   const bf16_t* Qw = Qp + (long)(wid * QBLK + r32) * LDQ + hi * 8;
; #pragma unroll
;   for (int d0 = 0; d0 < 8; ++d0) { const u32x4 raw = *reinterpret_cast<const u32x4*>(Qw + d0 * 16); u32x4 w;
; #pragma unroll
;     for (int p = 0; p < 4; ++p) w[p] = cvtpk(bf2f(raw[p] & 0xffffu) * C, bf2f(raw[p] >> 16) * C);
;     qr[d0] = *reinterpret_cast<bf16x8*>(&w); }
.LBB0_238:
	s_lshl_b32 s1, s74, 8
	s_lshl_b64 s[64:65], s[6:7], 13
	s_and_b32 s1, s1, 0x1f00
	s_or_b32 s64, s64, s1
	s_mul_hi_u32 s6, s64, 0x1800
	s_mul_i32 s7, s65, 0x1800
	s_mul_i32 s5, s64, 0x1800
	s_add_i32 s6, s6, s7
	v_readlane_b32 s7, v254, 60
	s_add_u32 s5, s7, s5
	v_readlane_b32 s7, v254, 61
	s_addc_u32 s7, s7, s6
	s_mul_i32 s6, s38, 0x180
	s_add_u32 s6, s5, s6
	s_addc_u32 s7, s7, 0
	v_and_b32_e32 v196, 31, v50
	s_lshl_b32 s39, s8, 5
	v_or_b32_e32 v1, s39, v196
	v_mov_b64_e32 v[2:3], s[6:7]
	s_movk_i32 s5, 0x1800
	v_mad_i64_i32 v[2:3], s[6:7], v1, s5, v[2:3]
	v_lshlrev_b32_e32 v194, 4, v49
	v_mov_b32_e32 v195, v0
	v_lshl_add_u64 v[2:3], v[2:3], 0, v[194:195]
	global_load_dwordx4 v[130:133], v[2:3], off
	global_load_dwordx4 v[134:137], v[2:3], off offset:32
	global_load_dwordx4 v[138:141], v[2:3], off offset:64
	global_load_dwordx4 v[142:145], v[2:3], off offset:96
	global_load_dwordx4 v[154:157], v[2:3], off offset:128
	global_load_dwordx4 v[150:153], v[2:3], off offset:160
	global_load_dwordx4 v[146:149], v[2:3], off offset:192
	global_load_dwordx4 v[158:161], v[2:3], off offset:224
	global_load_dwordx4 v[162:165], v[2:3], off offset:256
	global_load_dwordx4 v[166:169], v[2:3], off offset:288
	global_load_dwordx4 v[170:173], v[2:3], off offset:320
	global_load_dwordx4 v[174:177], v[2:3], off offset:352
	s_mov_b32 s6, 0x3dd53b94
	v_lshlrev_b32_e32 v204, 8, v196
	v_and_b32_e32 v51, 0xf0, v48
	v_add_u32_e32 v66, 0, v204
	s_waitcnt vmcnt(20)
	v_xad_u32 v56, v194, v51, v66
	v_lshlrev_b32_e32 v205, 7, v196
	s_and_b32 s0, s0, 0x3fffffc0
	s_lshl_b32 s0, s0, 2
	s_add_i32 s33, s0, 0
	s_add_i32 s33, s33, 0x1e000
	v_lshl_add_u32 v200, v196, 2, s33
	s_waitcnt vmcnt(11)
	v_lshlrev_b32_e32 v1, 16, v130
	v_and_b32_e32 v4, 0xffff0000, v130
	v_lshlrev_b32_e32 v8, 16, v131
	v_and_b32_e32 v5, 0xffff0000, v131
	v_lshlrev_b32_e32 v9, 16, v132
	v_and_b32_e32 v6, 0xffff0000, v132
	v_lshlrev_b32_e32 v10, 16, v133
	v_and_b32_e32 v7, 0xffff0000, v133
	v_mul_f32_e32 v4, 0x3dd53b94, v4
	v_mul_f32_e32 v5, 0x3dd53b94, v5
	v_mul_f32_e32 v6, 0x3dd53b94, v6
	v_mul_f32_e32 v7, 0x3dd53b94, v7
	v_mul_f32_e32 v1, 0x3dd53b94, v1
	v_mul_f32_e32 v8, 0x3dd53b94, v8
	v_mul_f32_e32 v9, 0x3dd53b94, v9
	v_mul_f32_e32 v10, 0x3dd53b94, v10
	v_cvt_pk_bf16_f32 v130, v1, v4
	v_cvt_pk_bf16_f32 v131, v8, v5
	v_cvt_pk_bf16_f32 v132, v9, v6
	v_cvt_pk_bf16_f32 v133, v10, v7
	s_waitcnt vmcnt(10)
	v_lshlrev_b32_e32 v1, 16, v134
	v_and_b32_e32 v4, 0xffff0000, v134
	v_lshlrev_b32_e32 v8, 16, v135
	v_and_b32_e32 v5, 0xffff0000, v135
	v_lshlrev_b32_e32 v9, 16, v136
	v_and_b32_e32 v6, 0xffff0000, v136
	v_lshlrev_b32_e32 v10, 16, v137
	v_and_b32_e32 v7, 0xffff0000, v137
	v_mul_f32_e32 v4, 0x3dd53b94, v4
	v_mul_f32_e32 v5, 0x3dd53b94, v5
	v_mul_f32_e32 v6, 0x3dd53b94, v6
	v_mul_f32_e32 v7, 0x3dd53b94, v7
	v_mul_f32_e32 v1, 0x3dd53b94, v1
	v_mul_f32_e32 v8, 0x3dd53b94, v8
	v_mul_f32_e32 v9, 0x3dd53b94, v9
	v_mul_f32_e32 v10, 0x3dd53b94, v10
	v_cvt_pk_bf16_f32 v134, v1, v4
	v_cvt_pk_bf16_f32 v135, v8, v5
	v_cvt_pk_bf16_f32 v136, v9, v6
	v_cvt_pk_bf16_f32 v137, v10, v7
	s_waitcnt vmcnt(9)
	v_lshlrev_b32_e32 v1, 16, v138
	v_and_b32_e32 v4, 0xffff0000, v138
	v_lshlrev_b32_e32 v8, 16, v139
	v_and_b32_e32 v5, 0xffff0000, v139
	v_lshlrev_b32_e32 v9, 16, v140
	v_and_b32_e32 v6, 0xffff0000, v140
	v_lshlrev_b32_e32 v10, 16, v141
	v_and_b32_e32 v7, 0xffff0000, v141
	v_mul_f32_e32 v4, 0x3dd53b94, v4
	v_mul_f32_e32 v5, 0x3dd53b94, v5
	v_mul_f32_e32 v6, 0x3dd53b94, v6
	v_mul_f32_e32 v7, 0x3dd53b94, v7
	v_mul_f32_e32 v1, 0x3dd53b94, v1
	v_mul_f32_e32 v8, 0x3dd53b94, v8
	v_mul_f32_e32 v9, 0x3dd53b94, v9
	v_mul_f32_e32 v10, 0x3dd53b94, v10
	v_cvt_pk_bf16_f32 v138, v1, v4
	v_cvt_pk_bf16_f32 v139, v8, v5
	v_cvt_pk_bf16_f32 v140, v9, v6
	v_cvt_pk_bf16_f32 v141, v10, v7
	s_waitcnt vmcnt(8)
	v_lshlrev_b32_e32 v1, 16, v142
	v_and_b32_e32 v4, 0xffff0000, v142
	v_lshlrev_b32_e32 v8, 16, v143
	v_and_b32_e32 v5, 0xffff0000, v143
	v_lshlrev_b32_e32 v9, 16, v144
	v_and_b32_e32 v6, 0xffff0000, v144
	v_lshlrev_b32_e32 v10, 16, v145
	v_and_b32_e32 v7, 0xffff0000, v145
	v_mul_f32_e32 v4, 0x3dd53b94, v4
	v_mul_f32_e32 v5, 0x3dd53b94, v5
	v_mul_f32_e32 v6, 0x3dd53b94, v6
	v_mul_f32_e32 v7, 0x3dd53b94, v7
	v_mul_f32_e32 v1, 0x3dd53b94, v1
	v_mul_f32_e32 v8, 0x3dd53b94, v8
	v_mul_f32_e32 v9, 0x3dd53b94, v9
	v_mul_f32_e32 v10, 0x3dd53b94, v10
	v_cvt_pk_bf16_f32 v142, v1, v4
	v_cvt_pk_bf16_f32 v143, v8, v5
	v_cvt_pk_bf16_f32 v144, v9, v6
	v_cvt_pk_bf16_f32 v145, v10, v7
	s_waitcnt vmcnt(7)
	v_lshlrev_b32_e32 v1, 16, v154
	v_and_b32_e32 v4, 0xffff0000, v154
	v_lshlrev_b32_e32 v8, 16, v155
	v_and_b32_e32 v5, 0xffff0000, v155
	v_lshlrev_b32_e32 v9, 16, v156
	v_and_b32_e32 v6, 0xffff0000, v156
	v_lshlrev_b32_e32 v10, 16, v157
	v_and_b32_e32 v7, 0xffff0000, v157
	v_mul_f32_e32 v4, 0x3dd53b94, v4
	v_mul_f32_e32 v5, 0x3dd53b94, v5
	v_mul_f32_e32 v6, 0x3dd53b94, v6
	v_mul_f32_e32 v7, 0x3dd53b94, v7
	v_mul_f32_e32 v1, 0x3dd53b94, v1
	v_mul_f32_e32 v8, 0x3dd53b94, v8
	v_mul_f32_e32 v9, 0x3dd53b94, v9
	v_mul_f32_e32 v10, 0x3dd53b94, v10
	v_cvt_pk_bf16_f32 v154, v1, v4
	v_cvt_pk_bf16_f32 v155, v8, v5
	v_cvt_pk_bf16_f32 v156, v9, v6
	v_cvt_pk_bf16_f32 v157, v10, v7
	s_waitcnt vmcnt(6)
	v_lshlrev_b32_e32 v1, 16, v150
	v_and_b32_e32 v4, 0xffff0000, v150
	v_lshlrev_b32_e32 v8, 16, v151
	v_and_b32_e32 v5, 0xffff0000, v151
	v_lshlrev_b32_e32 v9, 16, v152
	v_and_b32_e32 v6, 0xffff0000, v152
	v_lshlrev_b32_e32 v10, 16, v153
	v_and_b32_e32 v7, 0xffff0000, v153
	v_mul_f32_e32 v4, 0x3dd53b94, v4
	v_mul_f32_e32 v5, 0x3dd53b94, v5
	v_mul_f32_e32 v6, 0x3dd53b94, v6
	v_mul_f32_e32 v7, 0x3dd53b94, v7
	v_mul_f32_e32 v1, 0x3dd53b94, v1
	v_mul_f32_e32 v8, 0x3dd53b94, v8
	v_mul_f32_e32 v9, 0x3dd53b94, v9
	v_mul_f32_e32 v10, 0x3dd53b94, v10
	v_cvt_pk_bf16_f32 v150, v1, v4
	v_cvt_pk_bf16_f32 v151, v8, v5
	v_cvt_pk_bf16_f32 v152, v9, v6
	v_cvt_pk_bf16_f32 v153, v10, v7
	s_waitcnt vmcnt(5)
; __device__ __forceinline__ float bf2f(unsigned h) { return __uint_as_float(h << 16); }
; __device__ __forceinline__ void mla_unit(char* lds, const bf16_t* __restrict__ Qp, const bf16_t* __restrict__ Knp, const bf16_t* __restrict__ Vp, ...
;     ...
;   for (int d0 = 0; d0 < 8; ++d0) { const u32x4 raw = *reinterpret_cast<const u32x4*>(Qw + d0 * 16); u32x4 w;
; #pragma unroll
;     for (int p = 0; p < 4; ++p) w[p] = cvtpk(bf2f(raw[p] & 0xffffu) * C, bf2f(raw[p] >> 16) * C);
;     qr[d0] = *reinterpret_cast<bf16x8*>(&w); }
;   { const int pos = pos0 + wid * QBLK + r32;
; #pragma unroll
;     for (int d0 = 0; d0 < 4; ++d0) {
;       const u32x4 raw = *reinterpret_cast<const u32x4*>(Qw + 128 + d0 * 16);
;       const int i0 = d0 * 8 + hi * 4;
;       const f32x4 cc = *reinterpret_cast<const f32x4*>(cs_tab + pos * 32 + i0) * C, ss = *reinterpret_cast<const f32x4*>(sn_tab + pos * 32 + i0) * C;
;       u32x4 w;
; #pragma unroll
;       for (int p = 0; p < 4; ++p) { const float x1 = bf2f(raw[p] & 0xffffu), x2 = bf2f(raw[p] >> 16); w[p] = cvtpk(x1 * cc[p] - x2 * ss[p], x1 * ss[p] + x2 * cc[p]); }
;       qr[8 + d0] = *reinterpret_cast<bf16x8*>(&w);
;     } }
	v_lshlrev_b32_e32 v8, 16, v147
	v_lshlrev_b32_e32 v9, 16, v148
	v_and_b32_e32 v6, 0xffff0000, v148
	v_lshlrev_b32_e32 v10, 16, v149
	v_and_b32_e32 v7, 0xffff0000, v149
	v_lshlrev_b32_e32 v1, 16, v146
	v_and_b32_e32 v4, 0xffff0000, v146
	v_and_b32_e32 v5, 0xffff0000, v147
	v_mul_f32_e32 v8, 0x3dd53b94, v8
	v_mul_f32_e32 v9, 0x3dd53b94, v9
	v_mul_f32_e32 v6, 0x3dd53b94, v6
	v_mul_f32_e32 v7, 0x3dd53b94, v7
	v_mul_f32_e32 v1, 0x3dd53b94, v1
	v_mul_f32_e32 v4, 0x3dd53b94, v4
	v_mul_f32_e32 v5, 0x3dd53b94, v5
	v_mul_f32_e32 v10, 0x3dd53b94, v10
	v_cvt_pk_bf16_f32 v146, v1, v4
	v_cvt_pk_bf16_f32 v147, v8, v5
	v_cvt_pk_bf16_f32 v148, v9, v6
	v_cvt_pk_bf16_f32 v149, v10, v7
	v_or_b32_e32 v1, s1, v196
	v_add_lshl_u32 v4, v1, s39, 5
	v_ashrrev_i32_e32 v5, 31, v4
	v_lshlrev_b64 v[4:5], 2, v[4:5]
	v_lshl_add_u64 v[10:11], s[34:35], 0, v[4:5]
	v_lshl_add_u64 v[12:13], s[86:87], 0, v[4:5]
	v_lshl_add_u64 v[4:5], v[10:11], 0, v[194:195]
	v_lshl_add_u64 v[18:19], v[12:13], 0, v[194:195]
	s_add_i32 s1, 0, 0x18000
	v_add_u32_e32 v206, s1, v205
	s_waitcnt vmcnt(4)
	v_lshlrev_b32_e32 v1, 16, v158
	v_and_b32_e32 v6, 0xffff0000, v158
	v_lshlrev_b32_e32 v10, 16, v159
	v_and_b32_e32 v7, 0xffff0000, v159
	v_lshlrev_b32_e32 v11, 16, v160
	v_and_b32_e32 v8, 0xffff0000, v160
	v_lshlrev_b32_e32 v14, 16, v161
	v_and_b32_e32 v9, 0xffff0000, v161
	v_mul_f32_e32 v6, 0x3dd53b94, v6
	v_mul_f32_e32 v10, 0x3dd53b94, v10
	v_mul_f32_e32 v7, 0x3dd53b94, v7
	v_mul_f32_e32 v11, 0x3dd53b94, v11
	v_mul_f32_e32 v8, 0x3dd53b94, v8
	v_mul_f32_e32 v14, 0x3dd53b94, v14
	v_mul_f32_e32 v9, 0x3dd53b94, v9
	v_mul_f32_e32 v1, 0x3dd53b94, v1
	v_cvt_pk_bf16_f32 v158, v1, v6
	v_cvt_pk_bf16_f32 v159, v10, v7
	v_cvt_pk_bf16_f32 v160, v11, v8
	v_cvt_pk_bf16_f32 v161, v14, v9
	global_load_dwordx4 v[10:13], v[4:5], off
	global_load_dwordx4 v[14:17], v[18:19], off
	s_waitcnt vmcnt(1)
	v_mov_b32_e32 v22, v10
	s_waitcnt vmcnt(0)
	v_mov_b32_e32 v23, v14
	v_mov_b32_e32 v14, v11
	v_mov_b32_e32 v24, v12
	v_mov_b32_e32 v25, v16
	v_mov_b32_e32 v16, v13
	v_lshlrev_b32_e32 v20, 16, v162
	v_and_b32_e32 v21, 0xffff0000, v162
	v_lshlrev_b32_e32 v6, 16, v163
	v_and_b32_e32 v7, 0xffff0000, v163
	v_lshlrev_b32_e32 v10, 16, v164
	v_and_b32_e32 v11, 0xffff0000, v164
	v_lshlrev_b32_e32 v8, 16, v165
	v_and_b32_e32 v9, 0xffff0000, v165
	v_pk_mul_f32 v[12:13], v[22:23], s[6:7] op_sel_hi:[1,0]
	v_pk_mul_f32 v[14:15], v[14:15], s[6:7] op_sel_hi:[1,0]
	v_pk_mul_f32 v[22:23], v[24:25], s[6:7] op_sel_hi:[1,0]
	v_pk_mul_f32 v[16:17], v[16:17], s[6:7] op_sel_hi:[1,0]
	v_pk_mul_f32 v[24:25], v[12:13], v[20:21]
	v_pk_mul_f32 v[12:13], v[12:13], v[20:21] op_sel:[0,1] op_sel_hi:[1,0]
	v_pk_mul_f32 v[20:21], v[14:15], v[6:7]
	v_pk_mul_f32 v[6:7], v[14:15], v[6:7] op_sel:[0,1] op_sel_hi:[1,0]
	v_pk_mul_f32 v[14:15], v[22:23], v[10:11]
	v_pk_mul_f32 v[10:11], v[22:23], v[10:11] op_sel:[0,1] op_sel_hi:[1,0]
	v_pk_mul_f32 v[22:23], v[16:17], v[8:9]
	v_pk_mul_f32 v[8:9], v[16:17], v[8:9] op_sel:[0,1] op_sel_hi:[1,0]
	v_add_f32_e32 v12, v12, v13
	v_sub_f32_e32 v13, v20, v21
	v_add_f32_e32 v6, v6, v7
	v_sub_f32_e32 v7, v14, v15
	v_add_f32_e32 v10, v10, v11
	v_sub_f32_e32 v11, v22, v23
	v_add_f32_e32 v8, v8, v9
	v_sub_f32_e32 v1, v24, v25
	v_cvt_pk_bf16_f32 v162, v1, v12
	v_cvt_pk_bf16_f32 v163, v13, v6
	v_cvt_pk_bf16_f32 v164, v7, v10
	v_cvt_pk_bf16_f32 v165, v11, v8
	global_load_dwordx4 v[10:13], v[4:5], off offset:32
	global_load_dwordx4 v[14:17], v[18:19], off offset:32
	s_waitcnt vmcnt(2)
	v_lshlrev_b32_e32 v20, 16, v166
	s_waitcnt vmcnt(1)
	v_mov_b32_e32 v22, v10
	s_waitcnt vmcnt(0)
	v_mov_b32_e32 v23, v14
	v_mov_b32_e32 v14, v11
	v_mov_b32_e32 v24, v12
	v_mov_b32_e32 v25, v16
	v_mov_b32_e32 v16, v13
	v_and_b32_e32 v21, 0xffff0000, v166
	v_lshlrev_b32_e32 v6, 16, v167
	v_and_b32_e32 v7, 0xffff0000, v167
	v_lshlrev_b32_e32 v10, 16, v168
	v_and_b32_e32 v11, 0xffff0000, v168
	v_lshlrev_b32_e32 v8, 16, v169
	v_and_b32_e32 v9, 0xffff0000, v169
	v_pk_mul_f32 v[12:13], v[22:23], s[6:7] op_sel_hi:[1,0]
	v_pk_mul_f32 v[14:15], v[14:15], s[6:7] op_sel_hi:[1,0]
	v_pk_mul_f32 v[22:23], v[24:25], s[6:7] op_sel_hi:[1,0]
	v_pk_mul_f32 v[16:17], v[16:17], s[6:7] op_sel_hi:[1,0]
	v_pk_mul_f32 v[24:25], v[12:13], v[20:21]
	v_pk_mul_f32 v[12:13], v[12:13], v[20:21] op_sel:[0,1] op_sel_hi:[1,0]
	v_pk_mul_f32 v[20:21], v[14:15], v[6:7]
	v_pk_mul_f32 v[6:7], v[14:15], v[6:7] op_sel:[0,1] op_sel_hi:[1,0]
	v_pk_mul_f32 v[14:15], v[22:23], v[10:11]
	v_pk_mul_f32 v[10:11], v[22:23], v[10:11] op_sel:[0,1] op_sel_hi:[1,0]
	v_pk_mul_f32 v[22:23], v[16:17], v[8:9]
	v_pk_mul_f32 v[8:9], v[16:17], v[8:9] op_sel:[0,1] op_sel_hi:[1,0]
	v_add_f32_e32 v12, v12, v13
	v_sub_f32_e32 v13, v20, v21
	v_add_f32_e32 v6, v6, v7
	v_sub_f32_e32 v7, v14, v15
	v_add_f32_e32 v10, v10, v11
	v_sub_f32_e32 v11, v22, v23
	v_add_f32_e32 v8, v8, v9
	v_sub_f32_e32 v1, v24, v25
	v_cvt_pk_bf16_f32 v166, v1, v12
	v_cvt_pk_bf16_f32 v167, v13, v6
	v_cvt_pk_bf16_f32 v168, v7, v10
	v_cvt_pk_bf16_f32 v169, v11, v8
	global_load_dwordx4 v[10:13], v[4:5], off offset:64
	global_load_dwordx4 v[14:17], v[18:19], off offset:64
	s_waitcnt vmcnt(2)
	v_lshlrev_b32_e32 v20, 16, v170
	s_waitcnt vmcnt(1)
	v_mov_b32_e32 v22, v10
	s_waitcnt vmcnt(0)
; __device__ __forceinline__ float bf2f(unsigned h) { return __uint_as_float(h << 16); }
; __device__ __forceinline__ void qkt192n(f32x16& p0, f32x16& p1, const char* Ks, const char* Kr, const bf16x8* qr, const f32x16& negm, int r32, int hi) {
; #pragma unroll
;   for (int d0 = 0; d0 < 8; ++d0) { const int cb = d0 * 32 + hi * 16;
;     const bf16x8 b0 = *reinterpret_cast<const bf16x8*>(Ks + KSWZ(r32, cb));
;     const bf16x8 b1 = *reinterpret_cast<const bf16x8*>(Ks + KSWZ(32 + r32, cb));
;     if (d0 == 0) { p0 = __builtin_amdgcn_mfma_f32_32x32x16_bf16(b0, qr[0], negm, 0, 0, 0); p1 = __builtin_amdgcn_mfma_f32_32x32x16_bf16(b1, qr[0], negm, 0, 0, 0); }
;     else { p0 = __builtin_amdgcn_mfma_f32_32x32x16_bf16(b0, qr[d0], p0, 0, 0, 0); p1 = __builtin_amdgcn_mfma_f32_32x32x16_bf16(b1, qr[d0], p1, 0, 0, 0); } }
; __device__ __forceinline__ void mla_unit(char* lds, const bf16_t* __restrict__ Qp, const bf16_t* __restrict__ Knp, const bf16_t* __restrict__ Vp, ...
;     ...
;     for (int d0 = 0; d0 < 4; ++d0) {
;       const u32x4 raw = *reinterpret_cast<const u32x4*>(Qw + 128 + d0 * 16);
;       const int i0 = d0 * 8 + hi * 4;
;       const f32x4 cc = *reinterpret_cast<const f32x4*>(cs_tab + pos * 32 + i0) * C, ss = *reinterpret_cast<const f32x4*>(sn_tab + pos * 32 + i0) * C;
;       u32x4 w;
; #pragma unroll
;       for (int p = 0; p < 4; ++p) { const float x1 = bf2f(raw[p] & 0xffffu), x2 = bf2f(raw[p] >> 16); w[p] = cvtpk(x1 * cc[p] - x2 * ss[p], x1 * ss[p] + x2 * cc[p]); }
;       qr[8 + d0] = *reinterpret_cast<bf16x8*>(&w);
;     } }
;   f32x16 pA0, pA1, pB0, pB1; bf16x8 pa0, pa1, pa2, pa3;
;   constexpr float THRL = THR * 1.4426950408889634f;
;   float mhat = 0.f; f32x16 negm = f32x16{}; asm volatile("" : "+v"(negm));
	v_mov_b32_e32 v23, v14
	v_mov_b32_e32 v14, v11
	v_mov_b32_e32 v24, v12
	v_mov_b32_e32 v25, v16
	v_mov_b32_e32 v16, v13
	v_and_b32_e32 v21, 0xffff0000, v170
	v_lshlrev_b32_e32 v6, 16, v171
	v_and_b32_e32 v7, 0xffff0000, v171
	v_lshlrev_b32_e32 v10, 16, v172
	v_and_b32_e32 v11, 0xffff0000, v172
	v_lshlrev_b32_e32 v8, 16, v173
	v_and_b32_e32 v9, 0xffff0000, v173
	v_pk_mul_f32 v[12:13], v[22:23], s[6:7] op_sel_hi:[1,0]
	v_pk_mul_f32 v[14:15], v[14:15], s[6:7] op_sel_hi:[1,0]
	v_pk_mul_f32 v[22:23], v[24:25], s[6:7] op_sel_hi:[1,0]
	v_pk_mul_f32 v[16:17], v[16:17], s[6:7] op_sel_hi:[1,0]
	v_pk_mul_f32 v[24:25], v[12:13], v[20:21]
	v_pk_mul_f32 v[12:13], v[12:13], v[20:21] op_sel:[0,1] op_sel_hi:[1,0]
	v_pk_mul_f32 v[20:21], v[14:15], v[6:7]
	v_pk_mul_f32 v[6:7], v[14:15], v[6:7] op_sel:[0,1] op_sel_hi:[1,0]
	v_pk_mul_f32 v[14:15], v[22:23], v[10:11]
	v_pk_mul_f32 v[10:11], v[22:23], v[10:11] op_sel:[0,1] op_sel_hi:[1,0]
	v_pk_mul_f32 v[22:23], v[16:17], v[8:9]
	v_pk_mul_f32 v[8:9], v[16:17], v[8:9] op_sel:[0,1] op_sel_hi:[1,0]
	v_sub_f32_e32 v1, v24, v25
	v_add_f32_e32 v12, v12, v13
	v_sub_f32_e32 v13, v20, v21
	v_add_f32_e32 v6, v6, v7
	v_sub_f32_e32 v7, v14, v15
	v_add_f32_e32 v10, v10, v11
	v_sub_f32_e32 v11, v22, v23
	v_add_f32_e32 v8, v8, v9
	v_cvt_pk_bf16_f32 v170, v1, v12
	v_cvt_pk_bf16_f32 v171, v13, v6
	v_cvt_pk_bf16_f32 v172, v7, v10
	v_cvt_pk_bf16_f32 v173, v11, v8
	global_load_dwordx4 v[36:39], v[4:5], off offset:96
	global_load_dwordx4 v[40:43], v[18:19], off offset:96
	v_mov_b32_e32 v14, v0
	v_mov_b32_e32 v15, v0
	v_mov_b32_e32 v1, v0
	v_mov_b32_e32 v2, v0
	v_mov_b32_e32 v3, v0
	v_mov_b32_e32 v4, v0
	v_mov_b32_e32 v5, v0
	v_mov_b32_e32 v6, v0
	v_mov_b32_e32 v7, v0
	v_mov_b32_e32 v8, v0
	v_mov_b32_e32 v9, v0
	v_mov_b32_e32 v10, v0
	v_mov_b32_e32 v11, v0
	v_mov_b32_e32 v12, v0
	v_mov_b32_e32 v13, v0
	v_mov_b64_e32 v[30:31], v[14:15]
	v_mov_b64_e32 v[28:29], v[12:13]
	v_mov_b64_e32 v[26:27], v[10:11]
	v_mov_b64_e32 v[24:25], v[8:9]
	v_mov_b64_e32 v[22:23], v[6:7]
	v_mov_b64_e32 v[20:21], v[4:5]
	v_mov_b64_e32 v[18:19], v[2:3]
	v_mov_b64_e32 v[16:17], v[0:1]
	s_waitcnt vmcnt(2)
	v_lshlrev_b32_e32 v44, 16, v174
	s_waitcnt vmcnt(1)
	v_mov_b32_e32 v46, v36
	s_waitcnt vmcnt(0)
	v_mov_b32_e32 v47, v40
	v_mov_b32_e32 v40, v37
	v_mov_b32_e32 v52, v38
	v_mov_b32_e32 v53, v42
	v_mov_b32_e32 v42, v39
	v_and_b32_e32 v45, 0xffff0000, v174
	v_lshlrev_b32_e32 v32, 16, v175
	v_and_b32_e32 v33, 0xffff0000, v175
	v_lshlrev_b32_e32 v36, 16, v176
	v_and_b32_e32 v37, 0xffff0000, v176
	v_lshlrev_b32_e32 v34, 16, v177
	v_and_b32_e32 v35, 0xffff0000, v177
	v_pk_mul_f32 v[38:39], v[46:47], s[6:7] op_sel_hi:[1,0]
	v_pk_mul_f32 v[40:41], v[40:41], s[6:7] op_sel_hi:[1,0]
	v_pk_mul_f32 v[46:47], v[52:53], s[6:7] op_sel_hi:[1,0]
	v_pk_mul_f32 v[42:43], v[42:43], s[6:7] op_sel_hi:[1,0]
	v_pk_mul_f32 v[52:53], v[38:39], v[44:45]
	v_pk_mul_f32 v[38:39], v[38:39], v[44:45] op_sel:[0,1] op_sel_hi:[1,0]
	v_pk_mul_f32 v[44:45], v[40:41], v[32:33]
	v_pk_mul_f32 v[32:33], v[40:41], v[32:33] op_sel:[0,1] op_sel_hi:[1,0]
	v_pk_mul_f32 v[40:41], v[46:47], v[36:37]
	v_pk_mul_f32 v[36:37], v[46:47], v[36:37] op_sel:[0,1] op_sel_hi:[1,0]
	v_pk_mul_f32 v[46:47], v[42:43], v[34:35]
	v_pk_mul_f32 v[34:35], v[42:43], v[34:35] op_sel:[0,1] op_sel_hi:[1,0]
	v_sub_f32_e32 v42, v52, v53
	v_add_f32_e32 v38, v38, v39
	v_sub_f32_e32 v39, v44, v45
	v_add_f32_e32 v32, v32, v33
	v_sub_f32_e32 v33, v40, v41
	v_add_f32_e32 v36, v36, v37
	v_sub_f32_e32 v37, v46, v47
	v_add_f32_e32 v34, v34, v35
	v_cvt_pk_bf16_f32 v174, v42, v38
	v_cvt_pk_bf16_f32 v175, v39, v32
	v_cvt_pk_bf16_f32 v176, v33, v36
	v_cvt_pk_bf16_f32 v177, v37, v34
	s_waitcnt vmcnt(10) lgkmcnt(0)
	s_barrier
	ds_read_b128 v[52:55], v56 offset:49152
	ds_read_b128 v[56:59], v56 offset:57344
	s_waitcnt lgkmcnt(1)
	v_mfma_f32_32x32x16_bf16 v[32:47], v[52:55], v[130:133], v[16:31]
	v_or_b32_e32 v52, 32, v194
	v_xad_u32 v53, v52, v51, v66
	s_waitcnt lgkmcnt(0)
	v_mfma_f32_32x32x16_bf16 v[16:31], v[56:59], v[130:133], v[16:31]
	ds_read_b128 v[54:57], v53 offset:49152
	ds_read_b128 v[58:61], v53 offset:57344
	v_or_b32_e32 v53, 64, v194
	v_xad_u32 v62, v53, v51, v66
	s_waitcnt lgkmcnt(1)
	v_mfma_f32_32x32x16_bf16 v[32:47], v[54:57], v[134:137], v[32:47]
	s_waitcnt lgkmcnt(0)
	v_mfma_f32_32x32x16_bf16 v[16:31], v[58:61], v[134:137], v[16:31]
	ds_read_b128 v[54:57], v62 offset:49152
	ds_read_b128 v[58:61], v62 offset:57344
	s_waitcnt lgkmcnt(1)
	v_mfma_f32_32x32x16_bf16 v[32:47], v[54:57], v[138:141], v[32:47]
	v_or_b32_e32 v54, 0x60, v194
	v_xad_u32 v55, v54, v51, v66
	s_waitcnt lgkmcnt(0)
	v_mfma_f32_32x32x16_bf16 v[16:31], v[58:61], v[138:141], v[16:31]
	ds_read_b128 v[56:59], v55 offset:49152
	ds_read_b128 v[60:63], v55 offset:57344
	v_or_b32_e32 v55, 0x80, v194
	v_xad_u32 v64, v55, v51, v66
	s_waitcnt lgkmcnt(1)
	v_mfma_f32_32x32x16_bf16 v[32:47], v[56:59], v[142:145], v[32:47]
	s_waitcnt lgkmcnt(0)
	v_mfma_f32_32x32x16_bf16 v[16:31], v[60:63], v[142:145], v[16:31]
	ds_read_b128 v[56:59], v64 offset:49152
	ds_read_b128 v[60:63], v64 offset:57344
	s_waitcnt lgkmcnt(1)
	v_mfma_f32_32x32x16_bf16 v[32:47], v[56:59], v[154:157], v[32:47]
	v_or_b32_e32 v56, 0xa0, v194
	v_xad_u32 v57, v56, v51, v66
	s_waitcnt lgkmcnt(0)
	v_mfma_f32_32x32x16_bf16 v[16:31], v[60:63], v[154:157], v[16:31]
	ds_read_b128 v[58:61], v57 offset:49152
	ds_read_b128 v[62:65], v57 offset:57344
	v_or_b32_e32 v57, 0xc0, v194
	v_xad_u32 v67, v57, v51, v66
	s_waitcnt lgkmcnt(1)
	v_mfma_f32_32x32x16_bf16 v[32:47], v[58:61], v[150:153], v[32:47]
	s_waitcnt lgkmcnt(0)
	v_mfma_f32_32x32x16_bf16 v[16:31], v[62:65], v[150:153], v[16:31]
	ds_read_b128 v[58:61], v67 offset:49152
	ds_read_b128 v[62:65], v67 offset:57344
	s_waitcnt lgkmcnt(1)
; __device__ __forceinline__ void qkt192n(f32x16& p0, f32x16& p1, const char* Ks, const char* Kr, const bf16x8* qr, const f32x16& negm, int r32, int hi) {
; #pragma unroll
;   for (int d0 = 0; d0 < 8; ++d0) { const int cb = d0 * 32 + hi * 16;
;     const bf16x8 b0 = *reinterpret_cast<const bf16x8*>(Ks + KSWZ(r32, cb));
;     const bf16x8 b1 = *reinterpret_cast<const bf16x8*>(Ks + KSWZ(32 + r32, cb));
;     if (d0 == 0) { p0 = __builtin_amdgcn_mfma_f32_32x32x16_bf16(b0, qr[0], negm, 0, 0, 0); p1 = __builtin_amdgcn_mfma_f32_32x32x16_bf16(b1, qr[0], negm, 0, 0, 0); }
;     else { p0 = __builtin_amdgcn_mfma_f32_32x32x16_bf16(b0, qr[d0], p0, 0, 0, 0); p1 = __builtin_amdgcn_mfma_f32_32x32x16_bf16(b1, qr[d0], p1, 0, 0, 0); } }
; #pragma unroll
;   for (int d0 = 0; d0 < 4; ++d0) { const int cb = d0 * 32 + hi * 16;
;     const bf16x8 b0 = *reinterpret_cast<const bf16x8*>(Kr + RSWZ(r32, cb));
;     const bf16x8 b1 = *reinterpret_cast<const bf16x8*>(Kr + RSWZ(32 + r32, cb));
;     p0 = __builtin_amdgcn_mfma_f32_32x32x16_bf16(b0, qr[8 + d0], p0, 0, 0, 0);
;     p1 = __builtin_amdgcn_mfma_f32_32x32x16_bf16(b1, qr[8 + d0], p1, 0, 0, 0); }
	v_mfma_f32_32x32x16_bf16 v[32:47], v[58:61], v[146:149], v[32:47]
	v_or_b32_e32 v58, 0xe0, v194
	v_xad_u32 v59, v58, v51, v66
	s_waitcnt lgkmcnt(0)
	v_mfma_f32_32x32x16_bf16 v[16:31], v[62:65], v[146:149], v[16:31]
	ds_read_b128 v[60:63], v59 offset:49152
	ds_read_b128 v[64:67], v59 offset:57344
	v_lshlrev_b32_e32 v59, 3, v50
	v_and_b32_e32 v68, 0x70, v59
	v_xad_u32 v69, v194, v68, v206
	v_and_b32_e32 v50, 63, v50
	v_cmp_gt_u32_e64 s[40:41], 32, v50
	s_waitcnt lgkmcnt(1)
	v_mfma_f32_32x32x16_bf16 v[32:47], v[60:63], v[158:161], v[32:47]
	s_waitcnt lgkmcnt(0)
	v_mfma_f32_32x32x16_bf16 v[16:31], v[64:67], v[158:161], v[16:31]
	ds_read_b128 v[60:63], v69
	ds_read_b128 v[64:67], v69 offset:4096
	v_xad_u32 v69, v52, v68, v206
	s_waitcnt lgkmcnt(1)
	v_mfma_f32_32x32x16_bf16 v[32:47], v[60:63], v[162:165], v[32:47]
	s_waitcnt lgkmcnt(0)
	v_mfma_f32_32x32x16_bf16 v[16:31], v[64:67], v[162:165], v[16:31]
	ds_read_b128 v[60:63], v69
	ds_read_b128 v[64:67], v69 offset:4096
	v_xad_u32 v69, v53, v68, v206
	v_xad_u32 v68, v54, v68, v206
	s_waitcnt lgkmcnt(1)
	v_mfma_f32_32x32x16_bf16 v[32:47], v[60:63], v[166:169], v[32:47]
	s_waitcnt lgkmcnt(0)
	v_mfma_f32_32x32x16_bf16 v[16:31], v[64:67], v[166:169], v[16:31]
	ds_read_b128 v[60:63], v69
	ds_read_b128 v[64:67], v69 offset:4096
	s_waitcnt lgkmcnt(1)
	v_mfma_f32_32x32x16_bf16 v[32:47], v[60:63], v[170:173], v[32:47]
	s_waitcnt lgkmcnt(0)
	v_mfma_f32_32x32x16_bf16 v[16:31], v[64:67], v[170:173], v[16:31]
	ds_read_b128 v[60:63], v68
	ds_read_b128 v[64:67], v68 offset:4096
	s_waitcnt lgkmcnt(1)
	v_mfma_f32_32x32x16_bf16 v[32:47], v[60:63], v[174:177], v[32:47]
	s_waitcnt lgkmcnt(0)
; #define MX3(a, b, c) __builtin_fmaxf(__builtin_fmaxf((a), (b)), (c))
; #define MX3(a, b, c) __builtin_fmaxf(__builtin_fmaxf((a), (b)), (c))
; __device__ __forceinline__ float rowmax32(const f32x16& p0, const f32x16& p1) {
;   float a = MX3(p0[0], p0[1], p1[0]), b = MX3(p0[2], p0[3], p1[1]); a = MX3(a, p1[2], p1[3]);
; #pragma unroll
;   for (int r = 4; r < 16; r += 4) { a = MX3(a, p0[r], p0[r + 1]); b = MX3(b, p0[r + 2], p0[r + 3]); a = MX3(a, p1[r], p1[r + 1]); b = MX3(b, p1[r + 2], p1[r + 3]); }
;   float m = __builtin_fmaxf(a, b);
;   auto rr = __builtin_amdgcn_permlane32_swap(__float_as_uint(m), __float_as_uint(m), false, false);
;   return __builtin_fmaxf(__uint_as_float(rr[0]), __uint_as_float(rr[1]));
; }
; __device__ __forceinline__ void mla_unit(char* lds, const bf16_t* __restrict__ Qp, const bf16_t* __restrict__ Knp, const bf16_t* __restrict__ Vp, ...
;     ...
;   bool resc = false; float sum0 = 0.f;
	v_mfma_f32_32x32x16_bf16 v[16:31], v[64:67], v[174:177], v[16:31]
	s_nop 11
	v_max_f32_e32 v60, v32, v33
	v_max3_f32 v62, v34, v35, v17
	v_max3_f32 v60, v60, v16, v18
	v_max3_f32 v61, v62, v38, v39
	v_max3_f32 v60, v60, v19, v36
	v_max3_f32 v61, v61, v22, v23
	v_max3_f32 v60, v60, v37, v20
	v_max3_f32 v61, v61, v42, v43
	v_max3_f32 v60, v60, v21, v40
	v_max3_f32 v61, v61, v26, v27
	v_max3_f32 v60, v60, v41, v24
	v_max3_f32 v61, v61, v46, v47
	v_max3_f32 v60, v60, v25, v44
	v_max3_f32 v61, v61, v30, v31
	v_max3_f32 v60, v60, v45, v28
	v_max3_f32 v60, v60, v29, v61
	v_mov_b32_e32 v61, v60
	s_nop 1
	v_permlane32_swap_b32_e32 v60, v61
	v_max_f32_e32 v61, v60, v61
	v_exp_f32_e64 v60, -v61
	v_add_f32_e32 v203, 0, v61
	v_xor_b32_e32 v66, 0x80000000, v203
	v_mov_b32_e32 v67, v66
	v_mov_b32_e32 v68, v66
	v_mov_b32_e32 v69, v66
	v_mov_b32_e32 v70, v66
	v_mov_b32_e32 v71, v66
	v_mov_b32_e32 v72, v66
	v_mov_b32_e32 v73, v66
	v_mov_b32_e32 v74, v66
	v_mov_b32_e32 v75, v66
	v_mov_b32_e32 v76, v66
	v_mov_b32_e32 v77, v66
	v_mov_b32_e32 v78, v66
	v_mov_b32_e32 v79, v66
	v_mov_b32_e32 v80, v66
	v_mov_b32_e32 v81, v66
	s_and_saveexec_b64 s[6:7], s[40:41]
	ds_write_b32 v200, v60 offset:128
	s_or_b64 exec, exec, s[6:7]
	v_sub_f32_e32 v32, v32, v61
	v_sub_f32_e32 v33, v33, v61
	v_sub_f32_e32 v82, v16, v61
	v_exp_f32_e32 v16, v32
	v_sub_f32_e32 v34, v34, v61
	v_sub_f32_e32 v83, v17, v61
	v_exp_f32_e32 v17, v33
	v_sub_f32_e32 v35, v35, v61
	v_sub_f32_e32 v84, v18, v61
	v_exp_f32_e32 v18, v34
	v_sub_f32_e32 v36, v36, v61
	v_sub_f32_e32 v85, v19, v61
	v_exp_f32_e32 v19, v35
	v_sub_f32_e32 v37, v37, v61
	v_sub_f32_e32 v86, v20, v61
	v_exp_f32_e32 v20, v36
	v_add_f32_e32 v32, 0, v16
	v_sub_f32_e32 v38, v38, v61
	v_sub_f32_e32 v87, v21, v61
	v_exp_f32_e32 v21, v37
	v_add_f32_e32 v32, v17, v32
	v_sub_f32_e32 v39, v39, v61
	v_sub_f32_e32 v88, v22, v61
	v_exp_f32_e32 v22, v38
	v_add_f32_e32 v32, v18, v32
	v_sub_f32_e32 v40, v40, v61
	v_sub_f32_e32 v89, v23, v61
	v_exp_f32_e32 v23, v39
	v_add_f32_e32 v32, v19, v32
	v_sub_f32_e32 v41, v41, v61
	v_sub_f32_e32 v90, v24, v61
	v_exp_f32_e32 v24, v40
	v_add_f32_e32 v32, v20, v32
	v_sub_f32_e32 v42, v42, v61
	v_sub_f32_e32 v91, v25, v61
	v_exp_f32_e32 v25, v41
	v_add_f32_e32 v32, v21, v32
	v_sub_f32_e32 v43, v43, v61
	v_sub_f32_e32 v92, v26, v61
	v_exp_f32_e32 v26, v42
	v_add_f32_e32 v32, v22, v32
	v_sub_f32_e32 v44, v44, v61
	v_sub_f32_e32 v93, v27, v61
	v_exp_f32_e32 v27, v43
	v_add_f32_e32 v32, v23, v32
	v_sub_f32_e32 v45, v45, v61
	v_sub_f32_e32 v94, v28, v61
	v_exp_f32_e32 v28, v44
	v_add_f32_e32 v32, v24, v32
	s_lshr_b32 s69, s74, 5
	v_sub_f32_e32 v46, v46, v61
	v_sub_f32_e32 v95, v29, v61
	v_exp_f32_e32 v29, v45
	v_add_f32_e32 v32, v25, v32
	v_sub_f32_e32 v47, v47, v61
	v_sub_f32_e32 v96, v30, v61
	s_and_b32 s0, s69, 15
	v_exp_f32_e32 v30, v46
	v_add_f32_e32 v32, v26, v32
	s_movk_i32 s1, 0x70
	v_sub_f32_e32 v97, v31, v61
	s_lshl_b32 s0, s0, 23
	v_exp_f32_e32 v31, v47
	v_add_f32_e32 v32, v27, v32
	v_bitop3_b32 v221, v194, v59, s1 bitop3:0x78
	v_bitop3_b32 v209, v52, v59, s1 bitop3:0x78
	v_bitop3_b32 v208, v53, v59, s1 bitop3:0x78
	v_bitop3_b32 v207, v54, v59, s1 bitop3:0x78
	v_readlane_b32 s1, v254, 9
	v_lshlrev_b32_e32 v62, 4, v50
	v_add_f32_e32 v32, v28, v32
	s_add_u32 s36, s1, s36
	v_readlane_b32 s1, v254, 10
	v_lshlrev_b32_e32 v195, 2, v49
	v_lshlrev_b32_e32 v49, 3, v50
	v_and_b32_e32 v62, 0xc0, v62
	v_lshlrev_b32_e32 v50, 1, v50
	v_add_f32_e32 v32, v29, v32
	s_addc_u32 s37, s1, s37
	v_and_or_b32 v62, v49, 24, v62
	v_and_b32_e32 v50, 32, v50
	v_and_b32_e32 v49, 0x100, v49
	v_add_f32_e32 v32, v30, v32
	s_add_u32 s0, s0, s30
	v_or3_b32 v201, v62, v50, v49
	v_mul_f32_e32 v234, 0, v60
	v_add_f32_e32 v186, v31, v32
	v_cvt_pk_bf16_f32 v182, v16, v17
	v_cvt_pk_bf16_f32 v183, v18, v19
	v_cvt_pk_bf16_f32 v184, v20, v21
	v_cvt_pk_bf16_f32 v185, v22, v23
	v_cvt_pk_bf16_f32 v178, v24, v25
	v_cvt_pk_bf16_f32 v179, v26, v27
	v_cvt_pk_bf16_f32 v180, v28, v29
	v_cvt_pk_bf16_f32 v181, v30, v31
	v_bitop3_b32 v229, v194, v48, s53 bitop3:0x78
	v_bitop3_b32 v230, v194, v204, v51 bitop3:0xde
	v_bitop3_b32 v228, v52, v48, s53 bitop3:0x78
	v_bitop3_b32 v231, v52, v204, v51 bitop3:0xde
	v_bitop3_b32 v227, v53, v48, s53 bitop3:0x78
	v_bitop3_b32 v226, v54, v48, s53 bitop3:0x78
	v_bitop3_b32 v225, v55, v48, s53 bitop3:0x78
	v_bitop3_b32 v224, v56, v48, s53 bitop3:0x78
	v_bitop3_b32 v223, v57, v48, s53 bitop3:0x78
	v_bitop3_b32 v222, v58, v48, s53 bitop3:0x78
	s_addc_u32 s1, 0, s31
	v_readlane_b32 s12, v254, 35
	v_mov_b64_e32 v[64:65], v[14:15]
	v_mov_b64_e32 v[48:49], v[14:15]
	v_mov_b64_e32 v[32:33], v[14:15]
	v_readlane_b32 s13, v254, 36
	s_add_u32 s30, s12, s0
	v_mov_b64_e32 v[62:63], v[12:13]
	v_mov_b64_e32 v[60:61], v[10:11]
	v_mov_b64_e32 v[58:59], v[8:9]
	v_mov_b64_e32 v[56:57], v[6:7]
	v_mov_b64_e32 v[54:55], v[4:5]
	v_mov_b64_e32 v[52:53], v[2:3]
	v_mov_b64_e32 v[50:51], v[0:1]
	v_mov_b64_e32 v[46:47], v[12:13]
	v_mov_b64_e32 v[44:45], v[10:11]
	v_mov_b64_e32 v[42:43], v[8:9]
	v_mov_b64_e32 v[40:41], v[6:7]
	v_mov_b64_e32 v[38:39], v[4:5]
	v_mov_b64_e32 v[36:37], v[2:3]
	v_mov_b64_e32 v[34:35], v[0:1]
	v_mov_b64_e32 v[30:31], v[12:13]
	v_mov_b64_e32 v[28:29], v[10:11]
	v_mov_b64_e32 v[26:27], v[8:9]
	v_mov_b64_e32 v[24:25], v[6:7]
	v_mov_b64_e32 v[22:23], v[4:5]
	v_mov_b64_e32 v[20:21], v[2:3]
	v_mov_b64_e32 v[18:19], v[0:1]
	v_mov_b64_e32 v[16:17], v[14:15]
	s_mov_b32 s70, 1
	v_add_u32_e32 v202, 0, v201
	v_permlane32_swap_b32_e32 v182, v184
	v_permlane32_swap_b32_e32 v183, v185
	v_permlane32_swap_b32_e32 v178, v180
	v_permlane32_swap_b32_e32 v179, v181
	s_mov_b32 s77, 2
	v_add_u32_e32 v232, v229, v204
	v_add_u32_e32 v233, v228, v204
	s_addc_u32 s31, s13, s1
	s_mov_b32 s78, 0
	v_mov_b64_e32 v[14:15], v[12:13]
	v_mov_b64_e32 v[12:13], v[10:11]
	v_mov_b64_e32 v[10:11], v[8:9]
	v_mov_b64_e32 v[8:9], v[6:7]
	v_mov_b64_e32 v[6:7], v[4:5]
	v_mov_b64_e32 v[4:5], v[2:3]
	v_mov_b64_e32 v[2:3], v[0:1]
	s_mov_b32 s0, 0
	v_readlane_b32 s14, v254, 37
	v_readlane_b32 s15, v254, 38
